# mixer B: sink-logit load overlapped with the first K/V tile loads
# baseline (speedup 1.0000x reference)
; #define GAS __attribute__((address_space(1)))
; __device__ __forceinline__ void b_unit(const bf16_t* Z, bf16_t* MIX, const float* sinks, ldsp lds, int b, int kvh, int qb, unsigned& gt, int wave0) {
;     ...
;     bf16x8 qr[4]; q_load(qr, Z + tok * ZP0 + C_BQ + head * 64, hi);
;     float m = *(const GAS float*)(sinks + head) * LOG2E, l = (hi == 0) ? 1.f : 0.f;
;     f32x16 o[2], negm; splat16(negm, -m);
;     splat16(o[0], 0.f); splat16(o[1], 0.f);
;     const int n0 = qb >= 2 ? qb - 2 : 0;
;     const bf16_t* kvp = Z + ((size_t)b * T + key) * ZP0 + kvh * 64 + ch * 8;
;     u32x4 rk0 = ldg16(kvp + (size_t)(64 * n0) * ZP0 + C_BK), rv0 = ldg16(kvp + (size_t)(64 * n0) * ZP0 + C_BV), rk1 = rk0, rv1 = rv0;
;     if (n0 + 1 <= qb) { rk1 = ldg16(kvp + (size_t)(64 * (n0 + 1)) * ZP0 + C_BK); rv1 = ldg16(kvp + (size_t)(64 * (n0 + 1)) * ZP0 + C_BV); }
;     tile_store(lds + (gt & 1u) * 16384, rk0, rv0, key, ch);
;     if (n0 + 2 <= qb) { rk0 = ldg16(kvp + (size_t)(64 * (n0 + 2)) * ZP0 + C_BK); rv0 = ldg16(kvp + (size_t)(64 * (n0 + 2)) * ZP0 + C_BV); }
;     __syncthreads();
.LBB0_495:
	v_readlane_b32 s4, v254, 2
	v_readlane_b32 s5, v254, 3
	s_load_dwordx2 s[4:5], s[4:5], 0x60
	s_bfe_u32 s78, s2, 0x10006
	v_mbcnt_lo_u32_b32 v68, -1, 0
	v_mbcnt_hi_u32_b32 v68, -1, v68
	s_and_b32 s80, s2, 63
	v_bfe_u32 v16, v68, 3, 2
	v_lshl_or_b32 v50, s78, 2, v16
	v_lshlrev_b32_e32 v16, 2, v50
	s_waitcnt lgkmcnt(0)
	global_load_dword v56, v16, s[4:5]
	v_add_u32_e32 v48, s93, v68
	s_lshr_b32 s68, s2, 7
	v_readfirstlane_b32 s3, v48
	v_ashrrev_i32_e32 v64, 3, v48
	s_ashr_i32 s73, s3, 6
	s_lshl_b32 s79, s80, 6
	s_lshl_b64 s[70:71], s[68:69], 12
	v_ashrrev_i32_e32 v65, 31, v64
	s_lshl_b32 s72, s73, 3
	s_mov_b32 s4, 0x58000
	v_and_b32_e32 v69, 7, v68
	v_sub_u32_e64 v70, s80, 2 clamp
	v_lshlrev_b32_e32 v162, 7, v50
	v_lshl_add_u64 v[50:51], s[70:71], 0, v[64:65]
	s_add_i32 s6, s72, s79
	v_mul_lo_u32 v48, v70, s4
	v_mad_u64_u32 v[52:53], s[4:5], v50, s84, v[160:161]
	v_or_b32_e32 v166, s6, v69
	s_lshl_b32 s68, s78, 7
	v_mad_i32_i24 v53, v51, s84, v53
	v_ashrrev_i32_e32 v167, 31, v166
	v_lshl_add_u64 v[50:51], v[52:53], 0, s[68:69]
	v_lshl_add_u64 v[52:53], s[70:71], 0, v[166:167]
	v_mad_u64_u32 v[54:55], s[4:5], v52, s84, v[160:161]
	v_mad_i32_i24 v55, v53, s84, v55
	v_bfe_u32 v172, v68, 5, 1
	v_lshl_add_u64 v[52:53], v[54:55], 0, v[162:163]
	v_lshlrev_b32_e32 v162, 4, v69
	v_mov_b32_e32 v165, v163
	v_mov_b32_e32 v49, v163
	v_lshlrev_b32_e32 v164, 4, v172
	v_lshl_add_u64 v[168:169], v[50:51], 0, v[162:163]
	v_mov_b64_e32 v[30:31], v[14:15]
	v_mov_b64_e32 v[46:47], v[14:15]
	v_lshl_add_u64 v[52:53], v[52:53], 0, v[164:165]
	v_lshl_add_u64 v[66:67], v[168:169], 0, v[48:49]
	v_mov_b64_e32 v[28:29], v[12:13]
	v_mov_b64_e32 v[26:27], v[10:11]
	v_mov_b64_e32 v[24:25], v[8:9]
	v_mov_b64_e32 v[22:23], v[6:7]
	v_mov_b64_e32 v[20:21], v[4:5]
	v_mov_b64_e32 v[18:19], v[2:3]
	v_mov_b64_e32 v[16:17], v[0:1]
	v_mov_b64_e32 v[44:45], v[12:13]
	v_mov_b64_e32 v[42:43], v[10:11]
	v_mov_b64_e32 v[40:41], v[8:9]
	v_mov_b64_e32 v[38:39], v[6:7]
	v_mov_b64_e32 v[36:37], v[4:5]
	v_mov_b64_e32 v[34:35], v[2:3]
	v_mov_b64_e32 v[32:33], v[0:1]
	global_load_dwordx4 v[128:131], v[52:53], off offset:2560
	global_load_dwordx4 v[132:135], v[52:53], off offset:2592
	global_load_dwordx4 v[136:139], v[52:53], off offset:2624
	global_load_dwordx4 v[140:143], v[52:53], off offset:2656
	v_cmp_le_u32_e32 vcc, s80, v70
	v_readfirstlane_b32 s81, v70
	s_and_b64 vcc, exec, vcc
	global_load_dwordx4 v[144:147], v[66:67], off offset:3584
	global_load_dwordx4 v[148:151], v[66:67], off offset:3840
	s_cbranch_vccnz .Lb_pro_single
	v_add_co_u32_e32 v66, vcc, 0x58000, v66
	s_nop 1
	v_addc_co_u32_e32 v67, vcc, 0, v67, vcc
	global_load_dwordx4 v[152:155], v[66:67], off offset:3584
	global_load_dwordx4 v[156:159], v[66:67], off offset:3840
	s_waitcnt vmcnt(2)
	s_branch .LBB0_497

; #define GAS __attribute__((address_space(1)))
; __device__ __forceinline__ void b_unit(const bf16_t* Z, bf16_t* MIX, const float* sinks, ldsp lds, int b, int kvh, int qb, unsigned& gt, int wave0) {
;     ...
;     float m = *(const GAS float*)(sinks + head) * LOG2E, l = (hi == 0) ? 1.f : 0.f;
;     f32x16 o[2], negm; splat16(negm, -m);
;     splat16(o[0], 0.f); splat16(o[1], 0.f);
;     const int n0 = qb >= 2 ? qb - 2 : 0;
;     const bf16_t* kvp = Z + ((size_t)b * T + key) * ZP0 + kvh * 64 + ch * 8;
;     u32x4 rk0 = ldg16(kvp + (size_t)(64 * n0) * ZP0 + C_BK), rv0 = ldg16(kvp + (size_t)(64 * n0) * ZP0 + C_BV), rk1 = rk0, rv1 = rv0;
;     if (n0 + 1 <= qb) { rk1 = ldg16(kvp + (size_t)(64 * (n0 + 1)) * ZP0 + C_BK); rv1 = ldg16(kvp + (size_t)(64 * (n0 + 1)) * ZP0 + C_BV); }
;     tile_store(lds + (gt & 1u) * 16384, rk0, rv0, key, ch);
;     if (n0 + 2 <= qb) { rk0 = ldg16(kvp + (size_t)(64 * (n0 + 2)) * ZP0 + C_BK); rv0 = ldg16(kvp + (size_t)(64 * (n0 + 2)) * ZP0 + C_BV); }
;     __syncthreads();
.LBB0_497:
	v_mul_f32_e32 v173, 0x3fb8aa3b, v56
	v_xor_b32_e32 v48, 0x80000000, v173
	v_mov_b32_e32 v49, v48
	v_mov_b32_e32 v50, v48
	v_mov_b32_e32 v51, v48
	v_mov_b32_e32 v52, v48
	v_mov_b32_e32 v53, v48
	v_mov_b32_e32 v54, v48
	v_mov_b32_e32 v55, v48
	v_mov_b32_e32 v56, v48
	v_mov_b32_e32 v57, v48
	v_mov_b32_e32 v58, v48
	v_mov_b32_e32 v59, v48
	v_mov_b32_e32 v60, v48
	v_mov_b32_e32 v61, v48
	v_mov_b32_e32 v62, v48
	v_mov_b32_e32 v63, v48
	s_lshl_b32 s4, s82, 14
	s_and_b32 s4, s4, 0x4000
	v_lshlrev_b32_e32 v65, 5, v69
	v_lshlrev_b32_e32 v66, 4, v64
	s_add_i32 s4, s4, 0
	v_lshlrev_b32_e32 v175, 10, v69
	v_xor_b32_e32 v176, v66, v65
	v_lshlrev_b32_e32 v64, 6, v64
	v_add3_u32 v65, s4, v175, v176
	v_and_b32_e32 v177, 0x1000, v175
	v_and_b32_e32 v178, 0xfffffc00, v64
	ds_write_b128 v65, v[144:147]
	v_add3_u32 v65, s4, v177, v178
	v_and_b32_e32 v179, 0x3c0, v64
	v_and_b32_e32 v180, 48, v162
	s_add_i32 s4, s81, 2
	v_add3_u32 v64, v65, v179, v180
	s_cmp_gt_u32 s4, s80
	ds_write_b128 v64, v[148:151] offset:8192
	s_cbranch_scc1 .LBB0_499
	s_mul_i32 s68, s4, 0x58000
	v_lshl_add_u64 v[64:65], v[168:169], 0, s[68:69]
	global_load_dwordx4 v[144:147], v[64:65], off offset:3584
	global_load_dwordx4 v[148:151], v[64:65], off offset:3840
